# diff-attention loop: first V fragments of the next tile's P.V are read at the end of the previous step and the MFMAs start earlier in the softmax stream
# speedup vs baseline: 1.0653x; 1.0006x over previous
.Lnl_be:
	s_barrier
	s_cmp_lt_i32 s96, s9
	s_cbranch_scc0 .Lnl_noVe
	s_cmp_lt_i32 s11, 1
	s_cbranch_scc1 .Lnl_noVe
	s_sub_u32 s6, s50, 0x60000
	s_subb_u32 s7, s51, 0
	s_add_i32 s12, s10, 0x10000
	s_and_b32 s12, s12, 0x18000
	s_add_i32 s12, s90, s12
	v_lshl_add_u64 v[208:209], s[78:79], 0, v[172:173]
	v_lshl_add_u64 v[208:209], v[208:209], 0, s[6:7]
	s_mov_b32 m0, s12
	s_nop 0
	global_load_lds_dwordx4 v[208:209], off
	v_lshl_add_u64 v[208:209], s[78:79], 0, v[170:171]
	v_lshl_add_u64 v[208:209], v[208:209], 0, s[6:7]
	s_add_i32 m0, s12, 0x2000
	s_nop 0
	global_load_lds_dwordx4 v[208:209], off
.Lnl_noVe:
	s_add_i32 s97, s11, 3
	s_cmp_lt_i32 s97, s9
	s_cbranch_scc0 .Lnl_noKe
	s_add_i32 s12, s10, 0x18000
	s_and_b32 s12, s12, 0x18000
	s_add_i32 s12, s90, s12
	v_lshl_add_u64 v[208:209], s[78:79], 0, v[168:169]
	v_lshl_add_u64 v[208:209], v[208:209], 0, s[52:53]
	s_add_i32 m0, s12, 0x4000
	s_nop 0
	global_load_lds_dwordx4 v[208:209], off
	v_lshl_add_u64 v[208:209], s[78:79], 0, v[166:167]
	v_lshl_add_u64 v[208:209], v[208:209], 0, s[52:53]
	s_add_i32 m0, s12, 0x6000
	s_nop 0
	global_load_lds_dwordx4 v[208:209], off
.Lnl_noKe:
	s_cmp_eq_u32 s11, 0
	s_cbranch_scc0 .Lnl_me
	v_max_f32_e32 v206, v81, v81
	v_max_f32_e32 v207, v80, v80
	v_max_f32_e32 v206, v207, v206
	v_max3_f32 v206, v206, v82, v83
	v_max3_f32 v206, v206, v84, v85
	v_max3_f32 v206, v206, v86, v87
	v_max3_f32 v206, v206, v88, v89
	v_max3_f32 v206, v206, v90, v91
	v_max3_f32 v206, v206, v92, v93
	v_max3_f32 v206, v206, v94, v95
	v_max3_f32 v206, v206, v96, v97
	v_max3_f32 v206, v206, v98, v99
	v_max3_f32 v206, v206, v100, v101
	v_max3_f32 v206, v206, v102, v103
	v_max3_f32 v206, v206, v104, v105
	v_max3_f32 v206, v206, v106, v107
	v_max3_f32 v206, v206, v108, v109
	v_max3_f32 v206, v206, v110, v111
	v_mov_b32_e32 v207, v206
	s_nop 1
	v_permlane32_swap_b32_e32 v206, v207
	v_max_f32_e32 v207, v207, v207
	v_max_f32_e32 v206, v206, v206
	v_max_f32_e32 v206, v206, v207
	s_add_i32 s6, s10, 0x8000
	s_and_b32 s6, s6, 0x18000
	v_add_u32_e32 v0, s6, v175
	ds_read_b128 v[2:5], v0 offset:0
	ds_read_b128 v[6:9], v0 offset:8192
	v_add_u32_e32 v0, s6, v176
	ds_read_b128 v[10:13], v0 offset:0
	ds_read_b128 v[160:163], v0 offset:8192
	v_sub_f32_e32 v207, v206, v193
	v_cmp_ge_f32_e64 s[0:1], s27, v207
	v_max_f32_e32 v206, v206, v206
	v_max_f32_e32 v207, v193, v193
	v_max_f32_e32 v206, v207, v206
	s_cmp_eq_u64 s[0:1], exec
	s_cselect_b64 s[0:1], -1, 0
	v_cndmask_b32_e64 v14, v206, v193, s[0:1]
	v_mul_f32_e32 v207, 0xbe38aa3b, v14
	v_fmamk_f32 v174, v80, 0x3e38aa3b, v207
	v_exp_f32_e32 v80, v174
	v_fmamk_f32 v174, v81, 0x3e38aa3b, v207
	v_exp_f32_e32 v81, v174
	v_fmamk_f32 v174, v82, 0x3e38aa3b, v207
	v_exp_f32_e32 v82, v174
	s_waitcnt lgkmcnt(0)
	v_mfma_f32_32x32x16_bf16 v[112:127], v[2:5], v[144:147], 0
	v_fmamk_f32 v174, v83, 0x3e38aa3b, v207
	v_exp_f32_e32 v83, v174
	v_fmamk_f32 v174, v84, 0x3e38aa3b, v207
	v_exp_f32_e32 v84, v174
	v_fmamk_f32 v174, v85, 0x3e38aa3b, v207
	v_exp_f32_e32 v85, v174
	v_fmamk_f32 v174, v86, 0x3e38aa3b, v207
	v_exp_f32_e32 v86, v174
	v_fmamk_f32 v174, v87, 0x3e38aa3b, v207
	v_exp_f32_e32 v87, v174
	v_fmamk_f32 v174, v88, 0x3e38aa3b, v207
	v_exp_f32_e32 v88, v174
	v_fmamk_f32 v174, v89, 0x3e38aa3b, v207
	v_exp_f32_e32 v89, v174
	v_add_u32_e32 v0, s6, v177
	ds_read_b128 v[2:5], v0 offset:0
	v_mfma_f32_32x32x16_bf16 v[128:143], v[6:9], v[144:147], 0
	ds_read_b128 v[6:9], v0 offset:8192
	v_fmamk_f32 v174, v90, 0x3e38aa3b, v207
	v_exp_f32_e32 v90, v174
	v_fmamk_f32 v174, v91, 0x3e38aa3b, v207
	v_exp_f32_e32 v91, v174
	v_fmamk_f32 v174, v92, 0x3e38aa3b, v207
	v_exp_f32_e32 v92, v174
	v_fmamk_f32 v174, v93, 0x3e38aa3b, v207
	v_exp_f32_e32 v93, v174
	v_fmamk_f32 v174, v94, 0x3e38aa3b, v207
	v_exp_f32_e32 v94, v174
	v_fmamk_f32 v174, v95, 0x3e38aa3b, v207
	v_exp_f32_e32 v95, v174
	v_fmamk_f32 v174, v96, 0x3e38aa3b, v207
	v_exp_f32_e32 v96, v174
	v_fmamk_f32 v174, v97, 0x3e38aa3b, v207
	v_add_u32_e32 v0, s6, v189
	v_mfma_f32_32x32x16_bf16 v[112:127], v[10:13], v[148:151], v[112:127]
	ds_read_b128 v[10:13], v0 offset:0
	ds_read_b128 v[182:185], v0 offset:8192
	v_exp_f32_e32 v97, v174
	v_fmamk_f32 v174, v98, 0x3e38aa3b, v207
	v_exp_f32_e32 v98, v174
	v_fmamk_f32 v174, v99, 0x3e38aa3b, v207
	v_exp_f32_e32 v99, v174
	v_fmamk_f32 v174, v100, 0x3e38aa3b, v207
	v_exp_f32_e32 v100, v174
	v_fmamk_f32 v174, v101, 0x3e38aa3b, v207
	v_exp_f32_e32 v101, v174
	v_fmamk_f32 v174, v102, 0x3e38aa3b, v207
	v_exp_f32_e32 v102, v174
	v_fmamk_f32 v174, v103, 0x3e38aa3b, v207
	v_exp_f32_e32 v103, v174
	v_fmamk_f32 v174, v104, 0x3e38aa3b, v207
	s_waitcnt lgkmcnt(0)
	v_mfma_f32_32x32x16_bf16 v[128:143], v[160:163], v[148:151], v[128:143]
	v_exp_f32_e32 v104, v174
	v_fmamk_f32 v174, v105, 0x3e38aa3b, v207
	v_exp_f32_e32 v105, v174
	v_fmamk_f32 v174, v106, 0x3e38aa3b, v207
	v_exp_f32_e32 v106, v174
	v_fmamk_f32 v174, v107, 0x3e38aa3b, v207
	v_exp_f32_e32 v107, v174
	v_fmamk_f32 v174, v108, 0x3e38aa3b, v207
	v_exp_f32_e32 v108, v174
	v_fmamk_f32 v174, v109, 0x3e38aa3b, v207
	v_exp_f32_e32 v109, v174
	v_fmamk_f32 v174, v110, 0x3e38aa3b, v207
	v_exp_f32_e32 v110, v174
	v_fmamk_f32 v174, v111, 0x3e38aa3b, v207
	v_mfma_f32_32x32x16_bf16 v[112:127], v[2:5], v[152:155], v[112:127]
	v_exp_f32_e32 v111, v174
	v_sub_f32_e32 v206, v193, v206
	v_mul_f32_e32 v206, 0x3e38aa3b, v206
	v_exp_f32_e32 v206, v206
	v_add_f32_e32 v207, 0, v80
	v_cndmask_b32_e64 v194, v206, 1.0, s[0:1]
	v_mov_b32_e32 v193, v14
	v_add_f32_e32 v207, v81, v207
	v_add_f32_e32 v207, v82, v207
	v_add_f32_e32 v207, v83, v207
	v_add_f32_e32 v207, v84, v207
	v_add_f32_e32 v207, v85, v207
	v_add_f32_e32 v207, v86, v207
	v_add_f32_e32 v207, v87, v207
	v_add_f32_e32 v207, v88, v207
	v_mfma_f32_32x32x16_bf16 v[128:143], v[6:9], v[152:155], v[128:143]
	v_add_f32_e32 v207, v89, v207
	v_add_f32_e32 v207, v90, v207
	v_add_f32_e32 v207, v91, v207
	v_add_f32_e32 v207, v92, v207
	v_add_f32_e32 v207, v93, v207
	v_add_f32_e32 v207, v94, v207
	v_add_f32_e32 v207, v95, v207
	v_add_f32_e32 v207, v96, v207
	v_add_f32_e32 v207, v97, v207
	v_add_f32_e32 v207, v98, v207
	v_add_f32_e32 v207, v99, v207
	v_add_f32_e32 v207, v100, v207
	v_add_f32_e32 v207, v101, v207
	v_add_f32_e32 v207, v102, v207
	v_mfma_f32_32x32x16_bf16 v[112:127], v[10:13], v[156:159], v[112:127]
	v_add_f32_e32 v207, v103, v207
	v_add_f32_e32 v207, v104, v207
	v_add_f32_e32 v207, v105, v207
	v_add_f32_e32 v207, v106, v207
	v_add_f32_e32 v207, v107, v207
	v_add_f32_e32 v207, v108, v207
	v_add_f32_e32 v207, v109, v207
	v_add_f32_e32 v207, v110, v207
	v_add_f32_e32 v15, v111, v207
	v_mov_b32_e32 v195, v15
	v_cvt_pk_bf16_f32 v80, v80, v81
	v_cvt_pk_bf16_f32 v81, v82, v83
	v_cvt_pk_bf16_f32 v82, v84, v85
	v_cvt_pk_bf16_f32 v83, v86, v87
	v_mfma_f32_32x32x16_bf16 v[128:143], v[182:185], v[156:159], v[128:143]
	v_cvt_pk_bf16_f32 v84, v88, v89
	v_cvt_pk_bf16_f32 v85, v90, v91
	v_cvt_pk_bf16_f32 v86, v92, v93
	v_cvt_pk_bf16_f32 v87, v94, v95
	v_cvt_pk_bf16_f32 v88, v96, v97
	v_cvt_pk_bf16_f32 v89, v98, v99
	v_cvt_pk_bf16_f32 v90, v100, v101
	v_cvt_pk_bf16_f32 v91, v102, v103
	v_cvt_pk_bf16_f32 v92, v104, v105
	v_cvt_pk_bf16_f32 v93, v106, v107
	v_cvt_pk_bf16_f32 v94, v108, v109
	v_cvt_pk_bf16_f32 v95, v110, v111
	s_nop 1
	v_permlane32_swap_b32_e32 v15, v195
	v_permlane32_swap_b32_e32 v80, v82
	v_permlane32_swap_b32_e32 v81, v83
	v_permlane32_swap_b32_e32 v84, v86
	v_permlane32_swap_b32_e32 v85, v87
	v_permlane32_swap_b32_e32 v88, v90
	v_permlane32_swap_b32_e32 v89, v91
	v_permlane32_swap_b32_e32 v92, v94
	v_permlane32_swap_b32_e32 v93, v95
	v_add_f32_e32 v15, v15, v195
	v_fmac_f32_e32 v15, v192, v194
	v_mov_b32_e32 v192, v15
	s_add_i32 s0, s10, 0x0
	s_and_b32 s0, s0, 0x18000
	v_add_u32_e32 v13, s0, v191
	ds_read_b64_tr_b16 v[96:97], v13 offset:0
	ds_read_b64_tr_b16 v[98:99], v13 offset:2048
	ds_read_b64_tr_b16 v[100:101], v13 offset:512
	ds_read_b64_tr_b16 v[102:103], v13 offset:2560
	ds_read_b64_tr_b16 v[104:105], v13 offset:1024
	ds_read_b64_tr_b16 v[106:107], v13 offset:3072
	ds_read_b64_tr_b16 v[108:109], v13 offset:1536
	ds_read_b64_tr_b16 v[110:111], v13 offset:3584
	v_mov_b32_e32 v194, 1.0
	s_branch .Lnl_qe

.Lnl_nors_e:
	v_max_f32_e32 v206, v81, v81
	v_max_f32_e32 v207, v80, v80
	v_max_f32_e32 v206, v207, v206
	v_max3_f32 v206, v206, v82, v83
	v_max3_f32 v206, v206, v84, v85
	v_max3_f32 v206, v206, v86, v87
	v_max3_f32 v206, v206, v88, v89
	v_max3_f32 v206, v206, v90, v91
	v_max3_f32 v206, v206, v92, v93
	v_max3_f32 v206, v206, v94, v95
	v_max3_f32 v206, v206, v96, v97
	v_max3_f32 v206, v206, v98, v99
	s_waitcnt lgkmcnt(0)
	v_max3_f32 v206, v206, v100, v101
	v_max3_f32 v206, v206, v102, v103
	v_max3_f32 v206, v206, v104, v105
	v_max3_f32 v206, v206, v106, v107
	v_mfma_f32_32x32x16_bf16 v[64:79], v[128:131], v[112:115], v[64:79]
	v_max3_f32 v206, v206, v108, v109
	v_max3_f32 v206, v206, v110, v111
	v_mov_b32_e32 v207, v206
	s_nop 1
	ds_read_b64_tr_b16 v[160:161], v13 offset:4096
	ds_read_b64_tr_b16 v[162:163], v13 offset:6144
	ds_read_b64_tr_b16 v[182:183], v13 offset:4608
	ds_read_b64_tr_b16 v[184:185], v13 offset:6656
	ds_read_b64_tr_b16 v[198:199], v13 offset:5120
	ds_read_b64_tr_b16 v[200:201], v13 offset:7168
	ds_read_b64_tr_b16 v[202:203], v13 offset:5632
	ds_read_b64_tr_b16 v[204:205], v13 offset:7680
	v_permlane32_swap_b32_e32 v206, v207
	v_max_f32_e32 v207, v207, v207
	v_max_f32_e32 v206, v206, v206
	v_max_f32_e32 v206, v206, v207
	v_sub_f32_e32 v207, v206, v193
	v_mfma_f32_32x32x16_bf16 v[48:63], v[132:135], v[112:115], v[48:63]
	v_cmp_ge_f32_e64 s[0:1], s27, v207
	v_max_f32_e32 v206, v206, v206
	v_max_f32_e32 v207, v193, v193
	v_max_f32_e32 v206, v207, v206
	v_mfma_f32_32x32x16_bf16 v[32:47], v[136:139], v[112:115], v[32:47]
	s_cmp_eq_u64 s[0:1], exec
	s_cselect_b64 s[0:1], -1, 0
	v_cndmask_b32_e64 v14, v206, v193, s[0:1]
	v_mul_f32_e32 v207, 0xbe38aa3b, v14
	v_fmamk_f32 v174, v80, 0x3e38aa3b, v207
	v_exp_f32_e32 v80, v174
	v_mfma_f32_32x32x16_bf16 v[16:31], v[140:143], v[112:115], v[16:31]
	v_fmamk_f32 v174, v81, 0x3e38aa3b, v207
	v_exp_f32_e32 v81, v174
	v_fmamk_f32 v174, v82, 0x3e38aa3b, v207
	v_exp_f32_e32 v82, v174
	s_waitcnt lgkmcnt(0)
	v_fmamk_f32 v174, v83, 0x3e38aa3b, v207
	v_exp_f32_e32 v83, v174
	v_fmamk_f32 v174, v84, 0x3e38aa3b, v207
	v_exp_f32_e32 v84, v174
	v_mfma_f32_32x32x16_bf16 v[64:79], v[160:163], v[116:119], v[64:79]
	v_fmamk_f32 v174, v85, 0x3e38aa3b, v207
	v_exp_f32_e32 v85, v174
	v_fmamk_f32 v174, v86, 0x3e38aa3b, v207
	v_exp_f32_e32 v86, v174
	v_fmamk_f32 v174, v87, 0x3e38aa3b, v207
	ds_read_b64_tr_b16 v[128:129], v13 offset:8192
	ds_read_b64_tr_b16 v[130:131], v13 offset:10240
	ds_read_b64_tr_b16 v[132:133], v13 offset:8704
	ds_read_b64_tr_b16 v[134:135], v13 offset:10752
	ds_read_b64_tr_b16 v[136:137], v13 offset:9216
	ds_read_b64_tr_b16 v[138:139], v13 offset:11264
	ds_read_b64_tr_b16 v[140:141], v13 offset:9728
	ds_read_b64_tr_b16 v[142:143], v13 offset:11776
	v_exp_f32_e32 v87, v174
	v_fmamk_f32 v174, v88, 0x3e38aa3b, v207
	v_exp_f32_e32 v88, v174
	v_fmamk_f32 v174, v89, 0x3e38aa3b, v207
	v_mfma_f32_32x32x16_bf16 v[48:63], v[182:185], v[116:119], v[48:63]
	v_exp_f32_e32 v89, v174
	v_fmamk_f32 v174, v90, 0x3e38aa3b, v207
	v_exp_f32_e32 v90, v174
	v_fmamk_f32 v174, v91, 0x3e38aa3b, v207
	v_exp_f32_e32 v91, v174
	v_mfma_f32_32x32x16_bf16 v[32:47], v[198:201], v[116:119], v[32:47]
	v_fmamk_f32 v174, v92, 0x3e38aa3b, v207
	v_exp_f32_e32 v92, v174
	v_fmamk_f32 v174, v93, 0x3e38aa3b, v207
	v_exp_f32_e32 v93, v174
	v_mfma_f32_32x32x16_bf16 v[16:31], v[202:205], v[116:119], v[16:31]
	v_fmamk_f32 v174, v94, 0x3e38aa3b, v207
	v_exp_f32_e32 v94, v174
	v_fmamk_f32 v174, v95, 0x3e38aa3b, v207
	v_exp_f32_e32 v95, v174
	s_waitcnt lgkmcnt(0)
	v_fmamk_f32 v174, v96, 0x3e38aa3b, v207
	v_exp_f32_e32 v96, v174
	v_fmamk_f32 v174, v97, 0x3e38aa3b, v207
	v_exp_f32_e32 v97, v174
	v_fmamk_f32 v174, v98, 0x3e38aa3b, v207
	v_mfma_f32_32x32x16_bf16 v[64:79], v[128:131], v[120:123], v[64:79]
	v_exp_f32_e32 v98, v174
	v_fmamk_f32 v174, v99, 0x3e38aa3b, v207
	v_exp_f32_e32 v99, v174
	v_fmamk_f32 v174, v100, 0x3e38aa3b, v207
	ds_read_b64_tr_b16 v[160:161], v13 offset:12288
	ds_read_b64_tr_b16 v[162:163], v13 offset:14336
	ds_read_b64_tr_b16 v[182:183], v13 offset:12800
	ds_read_b64_tr_b16 v[184:185], v13 offset:14848
	ds_read_b64_tr_b16 v[198:199], v13 offset:13312
	ds_read_b64_tr_b16 v[200:201], v13 offset:15360
	ds_read_b64_tr_b16 v[202:203], v13 offset:13824
	ds_read_b64_tr_b16 v[204:205], v13 offset:15872
	v_exp_f32_e32 v100, v174
	v_fmamk_f32 v174, v101, 0x3e38aa3b, v207
	v_exp_f32_e32 v101, v174
	v_fmamk_f32 v174, v102, 0x3e38aa3b, v207
	v_exp_f32_e32 v102, v174
	v_mfma_f32_32x32x16_bf16 v[48:63], v[132:135], v[120:123], v[48:63]
	v_fmamk_f32 v174, v103, 0x3e38aa3b, v207
	v_exp_f32_e32 v103, v174
	v_fmamk_f32 v174, v104, 0x3e38aa3b, v207
	v_exp_f32_e32 v104, v174
	v_mfma_f32_32x32x16_bf16 v[32:47], v[136:139], v[120:123], v[32:47]
	v_fmamk_f32 v174, v105, 0x3e38aa3b, v207
	v_exp_f32_e32 v105, v174
	v_fmamk_f32 v174, v106, 0x3e38aa3b, v207
	v_exp_f32_e32 v106, v174
	v_mfma_f32_32x32x16_bf16 v[16:31], v[140:143], v[120:123], v[16:31]
	v_fmamk_f32 v174, v107, 0x3e38aa3b, v207
	v_exp_f32_e32 v107, v174
	v_fmamk_f32 v174, v108, 0x3e38aa3b, v207
	v_exp_f32_e32 v108, v174
	v_fmamk_f32 v174, v109, 0x3e38aa3b, v207
	s_waitcnt lgkmcnt(0)
	v_exp_f32_e32 v109, v174
	v_fmamk_f32 v174, v110, 0x3e38aa3b, v207
	v_exp_f32_e32 v110, v174
	v_fmamk_f32 v174, v111, 0x3e38aa3b, v207
	v_mfma_f32_32x32x16_bf16 v[64:79], v[160:163], v[124:127], v[64:79]
	v_exp_f32_e32 v111, v174
	v_sub_f32_e32 v206, v193, v206
	v_mul_f32_e32 v206, 0x3e38aa3b, v206
	v_exp_f32_e32 v206, v206
	v_add_f32_e32 v207, 0, v80
	v_mfma_f32_32x32x16_bf16 v[48:63], v[182:185], v[124:127], v[48:63]
	v_cndmask_b32_e64 v194, v206, 1.0, s[0:1]
	v_mov_b32_e32 v193, v14
	v_add_f32_e32 v207, v81, v207
	v_add_f32_e32 v207, v82, v207
	v_mfma_f32_32x32x16_bf16 v[32:47], v[198:201], v[124:127], v[32:47]
	v_add_f32_e32 v207, v83, v207
	v_add_f32_e32 v207, v84, v207
	v_add_f32_e32 v207, v85, v207
	v_add_f32_e32 v207, v86, v207
	v_mfma_f32_32x32x16_bf16 v[16:31], v[202:205], v[124:127], v[16:31]
	v_add_f32_e32 v207, v87, v207
	v_add_f32_e32 v207, v88, v207
	v_add_f32_e32 v207, v89, v207
	v_add_f32_e32 v207, v90, v207
	v_add_f32_e32 v207, v91, v207
	s_add_i32 s6, s10, 0x8000
	s_and_b32 s6, s6, 0x18000
	v_add_u32_e32 v0, s6, v175
	ds_read_b128 v[2:5], v0 offset:0
	ds_read_b128 v[6:9], v0 offset:8192
	v_add_u32_e32 v0, s6, v176
	ds_read_b128 v[10:13], v0 offset:0
	ds_read_b128 v[160:163], v0 offset:8192
	v_add_f32_e32 v207, v92, v207
	v_add_f32_e32 v207, v93, v207
	v_add_f32_e32 v207, v94, v207
	v_add_f32_e32 v207, v95, v207
	s_waitcnt lgkmcnt(0)
	v_mfma_f32_32x32x16_bf16 v[112:127], v[2:5], v[144:147], 0
	v_add_f32_e32 v207, v96, v207
	v_add_f32_e32 v207, v97, v207
	v_add_f32_e32 v207, v98, v207
	v_add_f32_e32 v207, v99, v207
	v_add_f32_e32 v207, v100, v207
	v_add_u32_e32 v0, s6, v177
	ds_read_b128 v[2:5], v0 offset:0
	v_mfma_f32_32x32x16_bf16 v[128:143], v[6:9], v[144:147], 0
	ds_read_b128 v[6:9], v0 offset:8192
	v_add_f32_e32 v207, v101, v207
	v_add_f32_e32 v207, v102, v207
	v_add_f32_e32 v207, v103, v207
	v_add_f32_e32 v207, v104, v207
	v_add_u32_e32 v0, s6, v189
	v_mfma_f32_32x32x16_bf16 v[112:127], v[10:13], v[148:151], v[112:127]
	ds_read_b128 v[10:13], v0 offset:0
	ds_read_b128 v[182:185], v0 offset:8192
	v_add_f32_e32 v207, v105, v207
	v_add_f32_e32 v207, v106, v207
	v_add_f32_e32 v207, v107, v207
	v_add_f32_e32 v207, v108, v207
	s_waitcnt lgkmcnt(0)
	v_mfma_f32_32x32x16_bf16 v[128:143], v[160:163], v[148:151], v[128:143]
	v_add_f32_e32 v207, v109, v207
	v_add_f32_e32 v207, v110, v207
	v_add_f32_e32 v15, v111, v207
	v_mov_b32_e32 v195, v15
	v_cvt_pk_bf16_f32 v80, v80, v81
	v_mfma_f32_32x32x16_bf16 v[112:127], v[2:5], v[152:155], v[112:127]
	v_cvt_pk_bf16_f32 v81, v82, v83
	v_cvt_pk_bf16_f32 v82, v84, v85
	v_cvt_pk_bf16_f32 v83, v86, v87
	v_cvt_pk_bf16_f32 v84, v88, v89
	v_mfma_f32_32x32x16_bf16 v[128:143], v[6:9], v[152:155], v[128:143]
	v_cvt_pk_bf16_f32 v85, v90, v91
	v_cvt_pk_bf16_f32 v86, v92, v93
	v_cvt_pk_bf16_f32 v87, v94, v95
	v_cvt_pk_bf16_f32 v88, v96, v97
	v_cvt_pk_bf16_f32 v89, v98, v99
	v_mfma_f32_32x32x16_bf16 v[112:127], v[10:13], v[156:159], v[112:127]
	v_cvt_pk_bf16_f32 v90, v100, v101
	v_cvt_pk_bf16_f32 v91, v102, v103
	v_cvt_pk_bf16_f32 v92, v104, v105
	v_cvt_pk_bf16_f32 v93, v106, v107
	v_mfma_f32_32x32x16_bf16 v[128:143], v[182:185], v[156:159], v[128:143]
	v_cvt_pk_bf16_f32 v94, v108, v109
	v_cvt_pk_bf16_f32 v95, v110, v111
	s_nop 1
	v_permlane32_swap_b32_e32 v15, v195
	v_permlane32_swap_b32_e32 v80, v82
	v_permlane32_swap_b32_e32 v81, v83
	v_permlane32_swap_b32_e32 v84, v86
	v_permlane32_swap_b32_e32 v85, v87
	v_permlane32_swap_b32_e32 v88, v90
	v_permlane32_swap_b32_e32 v89, v91
	v_permlane32_swap_b32_e32 v92, v94
	v_permlane32_swap_b32_e32 v93, v95
	v_add_f32_e32 v15, v15, v195
	v_fmac_f32_e32 v15, v192, v194
	v_mov_b32_e32 v192, v15
	s_add_i32 s0, s10, 0x0
	s_and_b32 s0, s0, 0x18000
	v_add_u32_e32 v13, s0, v191
	ds_read_b64_tr_b16 v[96:97], v13 offset:0
	ds_read_b64_tr_b16 v[98:99], v13 offset:2048
	ds_read_b64_tr_b16 v[100:101], v13 offset:512
	ds_read_b64_tr_b16 v[102:103], v13 offset:2560
	ds_read_b64_tr_b16 v[104:105], v13 offset:1024
	ds_read_b64_tr_b16 v[106:107], v13 offset:3072
	ds_read_b64_tr_b16 v[108:109], v13 offset:1536
	ds_read_b64_tr_b16 v[110:111], v13 offset:3584

.Lnl_bo:
	s_barrier
	s_cmp_lt_i32 s96, s9
	s_cbranch_scc0 .Lnl_noVo
	s_add_i32 s12, s10, 0x18000
	s_and_b32 s12, s12, 0x18000
	s_add_i32 s12, s90, s12
	v_lshl_add_u64 v[208:209], s[78:79], 0, v[172:173]
	v_lshl_add_u64 v[208:209], v[208:209], 0, s[50:51]
	s_mov_b32 m0, s12
	s_nop 0
	global_load_lds_dwordx4 v[208:209], off
	v_lshl_add_u64 v[208:209], s[78:79], 0, v[170:171]
	v_lshl_add_u64 v[208:209], v[208:209], 0, s[50:51]
	s_add_i32 m0, s12, 0x2000
	s_nop 0
	global_load_lds_dwordx4 v[208:209], off
.Lnl_noVo:
	s_add_i32 s97, s11, 4
	s_cmp_lt_i32 s97, s9
	s_cbranch_scc0 .Lnl_noKo
	s_add_i32 s12, s10, 0x0
	s_and_b32 s12, s12, 0x18000
	s_add_i32 s12, s90, s12
	v_lshl_add_u64 v[208:209], s[78:79], 0, v[168:169]
	v_lshl_add_u64 v[208:209], v[208:209], 0, s[56:57]
	s_add_i32 m0, s12, 0x4000
	s_nop 0
	global_load_lds_dwordx4 v[208:209], off
	v_lshl_add_u64 v[208:209], s[78:79], 0, v[166:167]
	v_lshl_add_u64 v[208:209], v[208:209], 0, s[56:57]
	s_add_i32 m0, s12, 0x6000
	s_nop 0
	global_load_lds_dwordx4 v[208:209], off
.Lnl_noKo:
	s_add_i32 s12, s11, 2
	s_cmp_lt_i32 s12, s9
	s_cbranch_scc1 .Lnl_mo
	s_add_i32 s12, s11, 1
	s_cmp_lt_i32 s12, s8
	s_cbranch_scc1 .Lnl_mol
	v_cmp_gt_f32_e32 vcc, 1.0, v194
	s_cbranch_vccz .Lnl_nors_po
	v_pk_mul_f32 v[78:79], v[78:79], v[194:195] op_sel_hi:[1,0]
	v_pk_mul_f32 v[76:77], v[76:77], v[194:195] op_sel_hi:[1,0]
	v_pk_mul_f32 v[74:75], v[74:75], v[194:195] op_sel_hi:[1,0]
	v_pk_mul_f32 v[72:73], v[72:73], v[194:195] op_sel_hi:[1,0]
	v_pk_mul_f32 v[70:71], v[70:71], v[194:195] op_sel_hi:[1,0]
	v_pk_mul_f32 v[68:69], v[68:69], v[194:195] op_sel_hi:[1,0]
	v_pk_mul_f32 v[66:67], v[66:67], v[194:195] op_sel_hi:[1,0]
	v_pk_mul_f32 v[64:65], v[64:65], v[194:195] op_sel_hi:[1,0]
	v_pk_mul_f32 v[62:63], v[62:63], v[194:195] op_sel_hi:[1,0]
	v_pk_mul_f32 v[60:61], v[60:61], v[194:195] op_sel_hi:[1,0]
	v_pk_mul_f32 v[58:59], v[58:59], v[194:195] op_sel_hi:[1,0]
	v_pk_mul_f32 v[56:57], v[56:57], v[194:195] op_sel_hi:[1,0]
	v_pk_mul_f32 v[54:55], v[54:55], v[194:195] op_sel_hi:[1,0]
	v_pk_mul_f32 v[52:53], v[52:53], v[194:195] op_sel_hi:[1,0]
	v_pk_mul_f32 v[50:51], v[50:51], v[194:195] op_sel_hi:[1,0]
	v_pk_mul_f32 v[48:49], v[48:49], v[194:195] op_sel_hi:[1,0]
	v_pk_mul_f32 v[46:47], v[46:47], v[194:195] op_sel_hi:[1,0]
	v_pk_mul_f32 v[44:45], v[44:45], v[194:195] op_sel_hi:[1,0]
	v_pk_mul_f32 v[42:43], v[42:43], v[194:195] op_sel_hi:[1,0]
	v_pk_mul_f32 v[40:41], v[40:41], v[194:195] op_sel_hi:[1,0]
	v_pk_mul_f32 v[38:39], v[38:39], v[194:195] op_sel_hi:[1,0]
	v_pk_mul_f32 v[36:37], v[36:37], v[194:195] op_sel_hi:[1,0]
	v_pk_mul_f32 v[34:35], v[34:35], v[194:195] op_sel_hi:[1,0]
	v_pk_mul_f32 v[32:33], v[32:33], v[194:195] op_sel_hi:[1,0]
	v_pk_mul_f32 v[30:31], v[30:31], v[194:195] op_sel_hi:[1,0]
	v_pk_mul_f32 v[28:29], v[28:29], v[194:195] op_sel_hi:[1,0]
	v_pk_mul_f32 v[26:27], v[26:27], v[194:195] op_sel_hi:[1,0]
	v_pk_mul_f32 v[24:25], v[24:25], v[194:195] op_sel_hi:[1,0]
	v_pk_mul_f32 v[22:23], v[22:23], v[194:195] op_sel_hi:[1,0]
	v_pk_mul_f32 v[20:21], v[20:21], v[194:195] op_sel_hi:[1,0]
	v_pk_mul_f32 v[18:19], v[18:19], v[194:195] op_sel_hi:[1,0]
	v_pk_mul_f32 v[16:17], v[16:17], v[194:195] op_sel_hi:[1,0]
.Lnl_nors_po:
	s_waitcnt lgkmcnt(0)
	v_mfma_f32_32x32x16_bf16 v[64:79], v[96:99], v[80:83], v[64:79]
	ds_read_b64_tr_b16 v[160:161], v13 offset:4096
	ds_read_b64_tr_b16 v[162:163], v13 offset:6144
	ds_read_b64_tr_b16 v[182:183], v13 offset:4608
	ds_read_b64_tr_b16 v[184:185], v13 offset:6656
	ds_read_b64_tr_b16 v[198:199], v13 offset:5120
	ds_read_b64_tr_b16 v[200:201], v13 offset:7168
	ds_read_b64_tr_b16 v[202:203], v13 offset:5632
	ds_read_b64_tr_b16 v[204:205], v13 offset:7680
	v_mfma_f32_32x32x16_bf16 v[48:63], v[100:103], v[80:83], v[48:63]
	v_mfma_f32_32x32x16_bf16 v[32:47], v[104:107], v[80:83], v[32:47]
	v_mfma_f32_32x32x16_bf16 v[16:31], v[108:111], v[80:83], v[16:31]
	s_waitcnt lgkmcnt(0)
	v_mfma_f32_32x32x16_bf16 v[64:79], v[160:163], v[84:87], v[64:79]
	ds_read_b64_tr_b16 v[96:97], v13 offset:8192
	ds_read_b64_tr_b16 v[98:99], v13 offset:10240
	ds_read_b64_tr_b16 v[100:101], v13 offset:8704
	ds_read_b64_tr_b16 v[102:103], v13 offset:10752
	ds_read_b64_tr_b16 v[104:105], v13 offset:9216
	ds_read_b64_tr_b16 v[106:107], v13 offset:11264
	ds_read_b64_tr_b16 v[108:109], v13 offset:9728
	ds_read_b64_tr_b16 v[110:111], v13 offset:11776
	v_mfma_f32_32x32x16_bf16 v[48:63], v[182:185], v[84:87], v[48:63]
	v_mfma_f32_32x32x16_bf16 v[32:47], v[198:201], v[84:87], v[32:47]
	v_mfma_f32_32x32x16_bf16 v[16:31], v[202:205], v[84:87], v[16:31]
	s_waitcnt lgkmcnt(0)
	v_mfma_f32_32x32x16_bf16 v[64:79], v[96:99], v[88:91], v[64:79]
	ds_read_b64_tr_b16 v[160:161], v13 offset:12288
	ds_read_b64_tr_b16 v[162:163], v13 offset:14336
	ds_read_b64_tr_b16 v[182:183], v13 offset:12800
	ds_read_b64_tr_b16 v[184:185], v13 offset:14848
	ds_read_b64_tr_b16 v[198:199], v13 offset:13312
	ds_read_b64_tr_b16 v[200:201], v13 offset:15360
	ds_read_b64_tr_b16 v[202:203], v13 offset:13824
	ds_read_b64_tr_b16 v[204:205], v13 offset:15872
	v_mfma_f32_32x32x16_bf16 v[48:63], v[100:103], v[88:91], v[48:63]
	v_mfma_f32_32x32x16_bf16 v[32:47], v[104:107], v[88:91], v[32:47]
	v_mfma_f32_32x32x16_bf16 v[16:31], v[108:111], v[88:91], v[16:31]
	s_waitcnt lgkmcnt(0)
	v_mfma_f32_32x32x16_bf16 v[64:79], v[160:163], v[92:95], v[64:79]
	v_mfma_f32_32x32x16_bf16 v[48:63], v[182:185], v[92:95], v[48:63]
	v_mfma_f32_32x32x16_bf16 v[32:47], v[198:201], v[92:95], v[32:47]
	v_mfma_f32_32x32x16_bf16 v[16:31], v[202:205], v[92:95], v[16:31]
	s_add_i32 s0, s10, 0x8000
	s_and_b32 s0, s0, 0x18000
	v_add_u32_e32 v13, s0, v191
	ds_read_b64_tr_b16 v[128:129], v13 offset:0
	ds_read_b64_tr_b16 v[130:131], v13 offset:2048
	ds_read_b64_tr_b16 v[132:133], v13 offset:512
	ds_read_b64_tr_b16 v[134:135], v13 offset:2560
	ds_read_b64_tr_b16 v[136:137], v13 offset:1024
	ds_read_b64_tr_b16 v[138:139], v13 offset:3072
	ds_read_b64_tr_b16 v[140:141], v13 offset:1536
	ds_read_b64_tr_b16 v[142:143], v13 offset:3584
	s_branch .Lnl_qo

.Lnl_nors_ol:
	v_max_f32_e32 v206, v113, v113
	v_max_f32_e32 v207, v112, v112
	v_max_f32_e32 v206, v207, v206
	v_max3_f32 v206, v206, v114, v115
	v_max3_f32 v206, v206, v116, v117
	v_max3_f32 v206, v206, v118, v119
	v_max3_f32 v206, v206, v120, v121
	v_max3_f32 v206, v206, v122, v123
	v_max3_f32 v206, v206, v124, v125
	v_max3_f32 v206, v206, v126, v127
	v_max3_f32 v206, v206, v128, v129
	v_max3_f32 v206, v206, v130, v131
	s_waitcnt lgkmcnt(0)
	v_max3_f32 v206, v206, v132, v133
	v_max3_f32 v206, v206, v134, v135
	v_max3_f32 v206, v206, v136, v137
	v_max3_f32 v206, v206, v138, v139
	v_max3_f32 v206, v206, v140, v141
	v_max3_f32 v206, v206, v142, v143
	v_mfma_f32_32x32x16_bf16 v[64:79], v[96:99], v[80:83], v[64:79]
	v_mov_b32_e32 v207, v206
	s_nop 1
	v_permlane32_swap_b32_e32 v206, v207
	v_max_f32_e32 v207, v207, v207
	v_max_f32_e32 v206, v206, v206
	v_max_f32_e32 v206, v206, v207
	ds_read_b64_tr_b16 v[160:161], v13 offset:4096
	ds_read_b64_tr_b16 v[162:163], v13 offset:6144
	ds_read_b64_tr_b16 v[182:183], v13 offset:4608
	ds_read_b64_tr_b16 v[184:185], v13 offset:6656
	ds_read_b64_tr_b16 v[198:199], v13 offset:5120
	ds_read_b64_tr_b16 v[200:201], v13 offset:7168
	ds_read_b64_tr_b16 v[202:203], v13 offset:5632
	ds_read_b64_tr_b16 v[204:205], v13 offset:7680
	v_sub_f32_e32 v207, v206, v193
	v_cmp_ge_f32_e64 s[0:1], s27, v207
	v_max_f32_e32 v206, v206, v206
	v_max_f32_e32 v207, v193, v193
	v_max_f32_e32 v206, v207, v206
	s_cmp_eq_u64 s[0:1], exec
	s_cselect_b64 s[0:1], -1, 0
	v_mfma_f32_32x32x16_bf16 v[48:63], v[100:103], v[80:83], v[48:63]
	v_cndmask_b32_e64 v14, v206, v193, s[0:1]
	v_mul_f32_e32 v207, 0xbe38aa3b, v14
	v_fmamk_f32 v174, v112, 0x3e38aa3b, v207
	v_exp_f32_e32 v112, v174
	v_fmamk_f32 v174, v113, 0x3e38aa3b, v207
	v_exp_f32_e32 v113, v174
	v_mfma_f32_32x32x16_bf16 v[32:47], v[104:107], v[80:83], v[32:47]
	v_fmamk_f32 v174, v114, 0x3e38aa3b, v207
	v_exp_f32_e32 v114, v174
	v_fmamk_f32 v174, v115, 0x3e38aa3b, v207
	v_exp_f32_e32 v115, v174
	v_fmamk_f32 v174, v116, 0x3e38aa3b, v207
	v_exp_f32_e32 v116, v174
	v_mfma_f32_32x32x16_bf16 v[16:31], v[108:111], v[80:83], v[16:31]
	v_fmamk_f32 v174, v117, 0x3e38aa3b, v207
	v_exp_f32_e32 v117, v174
	v_fmamk_f32 v174, v118, 0x3e38aa3b, v207
	v_exp_f32_e32 v118, v174
	v_fmamk_f32 v174, v119, 0x3e38aa3b, v207
	v_exp_f32_e32 v119, v174
	s_waitcnt lgkmcnt(0)
	v_fmamk_f32 v174, v120, 0x3e38aa3b, v207
	v_exp_f32_e32 v120, v174
	v_fmamk_f32 v174, v121, 0x3e38aa3b, v207
	v_exp_f32_e32 v121, v174
	v_fmamk_f32 v174, v122, 0x3e38aa3b, v207
	v_exp_f32_e32 v122, v174
	v_mfma_f32_32x32x16_bf16 v[64:79], v[160:163], v[84:87], v[64:79]
	v_fmamk_f32 v174, v123, 0x3e38aa3b, v207
	v_exp_f32_e32 v123, v174
	v_fmamk_f32 v174, v124, 0x3e38aa3b, v207
	v_exp_f32_e32 v124, v174
	v_fmamk_f32 v174, v125, 0x3e38aa3b, v207
	v_exp_f32_e32 v125, v174
	v_fmamk_f32 v174, v126, 0x3e38aa3b, v207
	ds_read_b64_tr_b16 v[96:97], v13 offset:8192
	ds_read_b64_tr_b16 v[98:99], v13 offset:10240
	ds_read_b64_tr_b16 v[100:101], v13 offset:8704
	ds_read_b64_tr_b16 v[102:103], v13 offset:10752
	ds_read_b64_tr_b16 v[104:105], v13 offset:9216
	ds_read_b64_tr_b16 v[106:107], v13 offset:11264
	ds_read_b64_tr_b16 v[108:109], v13 offset:9728
	ds_read_b64_tr_b16 v[110:111], v13 offset:11776
	v_exp_f32_e32 v126, v174
	v_fmamk_f32 v174, v127, 0x3e38aa3b, v207
	v_exp_f32_e32 v127, v174
	v_fmamk_f32 v174, v128, 0x3e38aa3b, v207
	v_exp_f32_e32 v128, v174
	v_fmamk_f32 v174, v129, 0x3e38aa3b, v207
	v_mfma_f32_32x32x16_bf16 v[48:63], v[182:185], v[84:87], v[48:63]
	v_exp_f32_e32 v129, v174
	v_fmamk_f32 v174, v130, 0x3e38aa3b, v207
	v_exp_f32_e32 v130, v174
	v_fmamk_f32 v174, v131, 0x3e38aa3b, v207
	v_exp_f32_e32 v131, v174
	v_fmamk_f32 v174, v132, 0x3e38aa3b, v207
	v_mfma_f32_32x32x16_bf16 v[32:47], v[198:201], v[84:87], v[32:47]
	v_exp_f32_e32 v132, v174
	v_fmamk_f32 v174, v133, 0x3e38aa3b, v207
	v_exp_f32_e32 v133, v174
	v_fmamk_f32 v174, v134, 0x3e38aa3b, v207
	v_exp_f32_e32 v134, v174
	v_fmamk_f32 v174, v135, 0x3e38aa3b, v207
	v_mfma_f32_32x32x16_bf16 v[16:31], v[202:205], v[84:87], v[16:31]
	v_exp_f32_e32 v135, v174
	v_fmamk_f32 v174, v136, 0x3e38aa3b, v207
	v_exp_f32_e32 v136, v174
	v_fmamk_f32 v174, v137, 0x3e38aa3b, v207
	v_exp_f32_e32 v137, v174
	v_fmamk_f32 v174, v138, 0x3e38aa3b, v207
	s_waitcnt lgkmcnt(0)
	v_exp_f32_e32 v138, v174
	v_fmamk_f32 v174, v139, 0x3e38aa3b, v207
	v_exp_f32_e32 v139, v174
	v_fmamk_f32 v174, v140, 0x3e38aa3b, v207
	v_exp_f32_e32 v140, v174
	v_fmamk_f32 v174, v141, 0x3e38aa3b, v207
	v_mfma_f32_32x32x16_bf16 v[64:79], v[96:99], v[88:91], v[64:79]
	v_exp_f32_e32 v141, v174
	v_fmamk_f32 v174, v142, 0x3e38aa3b, v207
	v_exp_f32_e32 v142, v174
	v_fmamk_f32 v174, v143, 0x3e38aa3b, v207
	v_exp_f32_e32 v143, v174
	v_sub_f32_e32 v206, v193, v206
	ds_read_b64_tr_b16 v[160:161], v13 offset:12288
	ds_read_b64_tr_b16 v[162:163], v13 offset:14336
	ds_read_b64_tr_b16 v[182:183], v13 offset:12800
	ds_read_b64_tr_b16 v[184:185], v13 offset:14848
	ds_read_b64_tr_b16 v[198:199], v13 offset:13312
	ds_read_b64_tr_b16 v[200:201], v13 offset:15360
	ds_read_b64_tr_b16 v[202:203], v13 offset:13824
	ds_read_b64_tr_b16 v[204:205], v13 offset:15872
	v_mul_f32_e32 v206, 0x3e38aa3b, v206
	v_exp_f32_e32 v206, v206
	v_add_f32_e32 v207, 0, v112
	v_cndmask_b32_e64 v194, v206, 1.0, s[0:1]
	v_mov_b32_e32 v193, v14
	v_add_f32_e32 v207, v113, v207
	v_mfma_f32_32x32x16_bf16 v[48:63], v[100:103], v[88:91], v[48:63]
	v_add_f32_e32 v207, v114, v207
	v_add_f32_e32 v207, v115, v207
	v_add_f32_e32 v207, v116, v207
	v_add_f32_e32 v207, v117, v207
	v_add_f32_e32 v207, v118, v207
	v_add_f32_e32 v207, v119, v207
	v_add_f32_e32 v207, v120, v207
	v_mfma_f32_32x32x16_bf16 v[32:47], v[104:107], v[88:91], v[32:47]
	v_add_f32_e32 v207, v121, v207
	v_add_f32_e32 v207, v122, v207
	v_add_f32_e32 v207, v123, v207
	v_add_f32_e32 v207, v124, v207
	v_add_f32_e32 v207, v125, v207
	v_add_f32_e32 v207, v126, v207
	v_mfma_f32_32x32x16_bf16 v[16:31], v[108:111], v[88:91], v[16:31]
	v_add_f32_e32 v207, v127, v207
	v_add_f32_e32 v207, v128, v207
	v_add_f32_e32 v207, v129, v207
	v_add_f32_e32 v207, v130, v207
	v_add_f32_e32 v207, v131, v207
	v_add_f32_e32 v207, v132, v207
	s_waitcnt lgkmcnt(0)
	v_add_f32_e32 v207, v133, v207
	v_add_f32_e32 v207, v134, v207
	v_add_f32_e32 v207, v135, v207
	v_add_f32_e32 v207, v136, v207
	v_add_f32_e32 v207, v137, v207
	v_add_f32_e32 v207, v138, v207
	v_mfma_f32_32x32x16_bf16 v[64:79], v[160:163], v[92:95], v[64:79]
	v_add_f32_e32 v207, v139, v207
	v_add_f32_e32 v207, v140, v207
	v_add_f32_e32 v207, v141, v207
	v_add_f32_e32 v207, v142, v207
	v_add_f32_e32 v15, v143, v207
	v_mov_b32_e32 v195, v15
	v_mfma_f32_32x32x16_bf16 v[48:63], v[182:185], v[92:95], v[48:63]
	v_cvt_pk_bf16_f32 v112, v112, v113
	v_cvt_pk_bf16_f32 v113, v114, v115
	v_cvt_pk_bf16_f32 v114, v116, v117
	v_cvt_pk_bf16_f32 v115, v118, v119
	v_cvt_pk_bf16_f32 v116, v120, v121
	v_cvt_pk_bf16_f32 v117, v122, v123
	v_mfma_f32_32x32x16_bf16 v[32:47], v[198:201], v[92:95], v[32:47]
	v_cvt_pk_bf16_f32 v118, v124, v125
	v_cvt_pk_bf16_f32 v119, v126, v127
	v_cvt_pk_bf16_f32 v120, v128, v129
	v_cvt_pk_bf16_f32 v121, v130, v131
	v_cvt_pk_bf16_f32 v122, v132, v133
	v_cvt_pk_bf16_f32 v123, v134, v135
	v_mfma_f32_32x32x16_bf16 v[16:31], v[202:205], v[92:95], v[16:31]
	v_cvt_pk_bf16_f32 v124, v136, v137
	v_cvt_pk_bf16_f32 v125, v138, v139
	v_cvt_pk_bf16_f32 v126, v140, v141
	v_cvt_pk_bf16_f32 v127, v142, v143
	s_nop 1
	v_permlane32_swap_b32_e32 v15, v195
	v_permlane32_swap_b32_e32 v112, v114
	v_permlane32_swap_b32_e32 v113, v115
	v_permlane32_swap_b32_e32 v116, v118
	v_permlane32_swap_b32_e32 v117, v119
	v_permlane32_swap_b32_e32 v120, v122
	v_permlane32_swap_b32_e32 v121, v123
	v_permlane32_swap_b32_e32 v124, v126
	v_permlane32_swap_b32_e32 v125, v127
	v_add_f32_e32 v15, v15, v195
	v_fmac_f32_e32 v15, v192, v194
	v_mov_b32_e32 v192, v15
	s_add_i32 s0, s10, 0x8000
	s_and_b32 s0, s0, 0x18000
	v_add_u32_e32 v13, s0, v191
	ds_read_b64_tr_b16 v[128:129], v13 offset:0
	ds_read_b64_tr_b16 v[130:131], v13 offset:2048
	ds_read_b64_tr_b16 v[132:133], v13 offset:512
	ds_read_b64_tr_b16 v[134:135], v13 offset:2560
	ds_read_b64_tr_b16 v[136:137], v13 offset:1024
	ds_read_b64_tr_b16 v[138:139], v13 offset:3072
	ds_read_b64_tr_b16 v[140:141], v13 offset:1536
	ds_read_b64_tr_b16 v[142:143], v13 offset:3584
	s_branch .Lnl_qo

.Lnl_nors_o:
	v_max_f32_e32 v206, v113, v113
	v_max_f32_e32 v207, v112, v112
	v_max_f32_e32 v206, v207, v206
	v_max3_f32 v206, v206, v114, v115
	v_max3_f32 v206, v206, v116, v117
	v_max3_f32 v206, v206, v118, v119
	v_max3_f32 v206, v206, v120, v121
	v_max3_f32 v206, v206, v122, v123
	v_max3_f32 v206, v206, v124, v125
	v_max3_f32 v206, v206, v126, v127
	v_max3_f32 v206, v206, v128, v129
	v_max3_f32 v206, v206, v130, v131
	s_waitcnt lgkmcnt(0)
	v_max3_f32 v206, v206, v132, v133
	v_max3_f32 v206, v206, v134, v135
	v_max3_f32 v206, v206, v136, v137
	v_max3_f32 v206, v206, v138, v139
	v_mfma_f32_32x32x16_bf16 v[64:79], v[96:99], v[80:83], v[64:79]
	v_max3_f32 v206, v206, v140, v141
	v_max3_f32 v206, v206, v142, v143
	v_mov_b32_e32 v207, v206
	s_nop 1
	ds_read_b64_tr_b16 v[160:161], v13 offset:4096
	ds_read_b64_tr_b16 v[162:163], v13 offset:6144
	ds_read_b64_tr_b16 v[182:183], v13 offset:4608
	ds_read_b64_tr_b16 v[184:185], v13 offset:6656
	ds_read_b64_tr_b16 v[198:199], v13 offset:5120
	ds_read_b64_tr_b16 v[200:201], v13 offset:7168
	ds_read_b64_tr_b16 v[202:203], v13 offset:5632
	ds_read_b64_tr_b16 v[204:205], v13 offset:7680
	v_permlane32_swap_b32_e32 v206, v207
	v_max_f32_e32 v207, v207, v207
	v_max_f32_e32 v206, v206, v206
	v_max_f32_e32 v206, v206, v207
	v_sub_f32_e32 v207, v206, v193
	v_mfma_f32_32x32x16_bf16 v[48:63], v[100:103], v[80:83], v[48:63]
	v_cmp_ge_f32_e64 s[0:1], s27, v207
	v_max_f32_e32 v206, v206, v206
	v_max_f32_e32 v207, v193, v193
	v_max_f32_e32 v206, v207, v206
	v_mfma_f32_32x32x16_bf16 v[32:47], v[104:107], v[80:83], v[32:47]
	s_cmp_eq_u64 s[0:1], exec
	s_cselect_b64 s[0:1], -1, 0
	v_cndmask_b32_e64 v14, v206, v193, s[0:1]
	v_mul_f32_e32 v207, 0xbe38aa3b, v14
	v_fmamk_f32 v174, v112, 0x3e38aa3b, v207
	v_exp_f32_e32 v112, v174
	v_mfma_f32_32x32x16_bf16 v[16:31], v[108:111], v[80:83], v[16:31]
	v_fmamk_f32 v174, v113, 0x3e38aa3b, v207
	v_exp_f32_e32 v113, v174
	v_fmamk_f32 v174, v114, 0x3e38aa3b, v207
	v_exp_f32_e32 v114, v174
	s_waitcnt lgkmcnt(0)
	v_fmamk_f32 v174, v115, 0x3e38aa3b, v207
	v_exp_f32_e32 v115, v174
	v_fmamk_f32 v174, v116, 0x3e38aa3b, v207
	v_exp_f32_e32 v116, v174
	v_mfma_f32_32x32x16_bf16 v[64:79], v[160:163], v[84:87], v[64:79]
	v_fmamk_f32 v174, v117, 0x3e38aa3b, v207
	v_exp_f32_e32 v117, v174
	v_fmamk_f32 v174, v118, 0x3e38aa3b, v207
	v_exp_f32_e32 v118, v174
	v_fmamk_f32 v174, v119, 0x3e38aa3b, v207
	ds_read_b64_tr_b16 v[96:97], v13 offset:8192
	ds_read_b64_tr_b16 v[98:99], v13 offset:10240
	ds_read_b64_tr_b16 v[100:101], v13 offset:8704
	ds_read_b64_tr_b16 v[102:103], v13 offset:10752
	ds_read_b64_tr_b16 v[104:105], v13 offset:9216
	ds_read_b64_tr_b16 v[106:107], v13 offset:11264
	ds_read_b64_tr_b16 v[108:109], v13 offset:9728
	ds_read_b64_tr_b16 v[110:111], v13 offset:11776
	v_exp_f32_e32 v119, v174
	v_fmamk_f32 v174, v120, 0x3e38aa3b, v207
	v_exp_f32_e32 v120, v174
	v_fmamk_f32 v174, v121, 0x3e38aa3b, v207
	v_mfma_f32_32x32x16_bf16 v[48:63], v[182:185], v[84:87], v[48:63]
	v_exp_f32_e32 v121, v174
	v_fmamk_f32 v174, v122, 0x3e38aa3b, v207
	v_exp_f32_e32 v122, v174
	v_fmamk_f32 v174, v123, 0x3e38aa3b, v207
	v_exp_f32_e32 v123, v174
	v_mfma_f32_32x32x16_bf16 v[32:47], v[198:201], v[84:87], v[32:47]
	v_fmamk_f32 v174, v124, 0x3e38aa3b, v207
	v_exp_f32_e32 v124, v174
	v_fmamk_f32 v174, v125, 0x3e38aa3b, v207
	v_exp_f32_e32 v125, v174
	v_mfma_f32_32x32x16_bf16 v[16:31], v[202:205], v[84:87], v[16:31]
	v_fmamk_f32 v174, v126, 0x3e38aa3b, v207
	v_exp_f32_e32 v126, v174
	v_fmamk_f32 v174, v127, 0x3e38aa3b, v207
	v_exp_f32_e32 v127, v174
	s_waitcnt lgkmcnt(0)
	v_fmamk_f32 v174, v128, 0x3e38aa3b, v207
	v_exp_f32_e32 v128, v174
	v_fmamk_f32 v174, v129, 0x3e38aa3b, v207
	v_exp_f32_e32 v129, v174
	v_fmamk_f32 v174, v130, 0x3e38aa3b, v207
	v_mfma_f32_32x32x16_bf16 v[64:79], v[96:99], v[88:91], v[64:79]
	v_exp_f32_e32 v130, v174
	v_fmamk_f32 v174, v131, 0x3e38aa3b, v207
	v_exp_f32_e32 v131, v174
	v_fmamk_f32 v174, v132, 0x3e38aa3b, v207
	ds_read_b64_tr_b16 v[160:161], v13 offset:12288
	ds_read_b64_tr_b16 v[162:163], v13 offset:14336
	ds_read_b64_tr_b16 v[182:183], v13 offset:12800
	ds_read_b64_tr_b16 v[184:185], v13 offset:14848
	ds_read_b64_tr_b16 v[198:199], v13 offset:13312
	ds_read_b64_tr_b16 v[200:201], v13 offset:15360
	ds_read_b64_tr_b16 v[202:203], v13 offset:13824
	ds_read_b64_tr_b16 v[204:205], v13 offset:15872
	v_exp_f32_e32 v132, v174
	v_fmamk_f32 v174, v133, 0x3e38aa3b, v207
	v_exp_f32_e32 v133, v174
	v_fmamk_f32 v174, v134, 0x3e38aa3b, v207
	v_exp_f32_e32 v134, v174
	v_mfma_f32_32x32x16_bf16 v[48:63], v[100:103], v[88:91], v[48:63]
	v_fmamk_f32 v174, v135, 0x3e38aa3b, v207
	v_exp_f32_e32 v135, v174
	v_fmamk_f32 v174, v136, 0x3e38aa3b, v207
	v_exp_f32_e32 v136, v174
	v_mfma_f32_32x32x16_bf16 v[32:47], v[104:107], v[88:91], v[32:47]
	v_fmamk_f32 v174, v137, 0x3e38aa3b, v207
	v_exp_f32_e32 v137, v174
	v_fmamk_f32 v174, v138, 0x3e38aa3b, v207
	v_exp_f32_e32 v138, v174
	v_mfma_f32_32x32x16_bf16 v[16:31], v[108:111], v[88:91], v[16:31]
	v_fmamk_f32 v174, v139, 0x3e38aa3b, v207
	v_exp_f32_e32 v139, v174
	v_fmamk_f32 v174, v140, 0x3e38aa3b, v207
	v_exp_f32_e32 v140, v174
	v_fmamk_f32 v174, v141, 0x3e38aa3b, v207
	s_waitcnt lgkmcnt(0)
	v_exp_f32_e32 v141, v174
	v_fmamk_f32 v174, v142, 0x3e38aa3b, v207
	v_exp_f32_e32 v142, v174
	v_fmamk_f32 v174, v143, 0x3e38aa3b, v207
	v_mfma_f32_32x32x16_bf16 v[64:79], v[160:163], v[92:95], v[64:79]
	v_exp_f32_e32 v143, v174
	v_sub_f32_e32 v206, v193, v206
	v_mul_f32_e32 v206, 0x3e38aa3b, v206
	v_exp_f32_e32 v206, v206
	v_add_f32_e32 v207, 0, v112
	v_mfma_f32_32x32x16_bf16 v[48:63], v[182:185], v[92:95], v[48:63]
	v_cndmask_b32_e64 v194, v206, 1.0, s[0:1]
	v_mov_b32_e32 v193, v14
	v_add_f32_e32 v207, v113, v207
	v_add_f32_e32 v207, v114, v207
	v_mfma_f32_32x32x16_bf16 v[32:47], v[198:201], v[92:95], v[32:47]
	v_add_f32_e32 v207, v115, v207
	v_add_f32_e32 v207, v116, v207
	v_add_f32_e32 v207, v117, v207
	v_add_f32_e32 v207, v118, v207
	v_mfma_f32_32x32x16_bf16 v[16:31], v[202:205], v[92:95], v[16:31]
	v_add_f32_e32 v207, v119, v207
	v_add_f32_e32 v207, v120, v207
	v_add_f32_e32 v207, v121, v207
	v_add_f32_e32 v207, v122, v207
	v_add_f32_e32 v207, v123, v207
	s_add_i32 s6, s10, 0x10000
	s_and_b32 s6, s6, 0x18000
	v_add_u32_e32 v0, s6, v175
	ds_read_b128 v[2:5], v0 offset:0
	ds_read_b128 v[6:9], v0 offset:8192
	v_add_u32_e32 v0, s6, v176
	ds_read_b128 v[10:13], v0 offset:0
	ds_read_b128 v[160:163], v0 offset:8192
	v_add_f32_e32 v207, v124, v207
	v_add_f32_e32 v207, v125, v207
	v_add_f32_e32 v207, v126, v207
	v_add_f32_e32 v207, v127, v207
	s_waitcnt lgkmcnt(0)
	v_mfma_f32_32x32x16_bf16 v[80:95], v[2:5], v[144:147], 0
	v_add_f32_e32 v207, v128, v207
	v_add_f32_e32 v207, v129, v207
	v_add_f32_e32 v207, v130, v207
	v_add_f32_e32 v207, v131, v207
	v_add_f32_e32 v207, v132, v207
	v_add_u32_e32 v0, s6, v177
	ds_read_b128 v[2:5], v0 offset:0
	v_mfma_f32_32x32x16_bf16 v[96:111], v[6:9], v[144:147], 0
	ds_read_b128 v[6:9], v0 offset:8192
	v_add_f32_e32 v207, v133, v207
	v_add_f32_e32 v207, v134, v207
	v_add_f32_e32 v207, v135, v207
	v_add_f32_e32 v207, v136, v207
	v_add_u32_e32 v0, s6, v189
	v_mfma_f32_32x32x16_bf16 v[80:95], v[10:13], v[148:151], v[80:95]
	ds_read_b128 v[10:13], v0 offset:0
	ds_read_b128 v[182:185], v0 offset:8192
	v_add_f32_e32 v207, v137, v207
	v_add_f32_e32 v207, v138, v207
	v_add_f32_e32 v207, v139, v207
	v_add_f32_e32 v207, v140, v207
	s_waitcnt lgkmcnt(0)
	v_mfma_f32_32x32x16_bf16 v[96:111], v[160:163], v[148:151], v[96:111]
	v_add_f32_e32 v207, v141, v207
	v_add_f32_e32 v207, v142, v207
	v_add_f32_e32 v15, v143, v207
	v_mov_b32_e32 v195, v15
	v_cvt_pk_bf16_f32 v112, v112, v113
	v_mfma_f32_32x32x16_bf16 v[80:95], v[2:5], v[152:155], v[80:95]
	v_cvt_pk_bf16_f32 v113, v114, v115
	v_cvt_pk_bf16_f32 v114, v116, v117
	v_cvt_pk_bf16_f32 v115, v118, v119
	v_cvt_pk_bf16_f32 v116, v120, v121
	v_mfma_f32_32x32x16_bf16 v[96:111], v[6:9], v[152:155], v[96:111]
	v_cvt_pk_bf16_f32 v117, v122, v123
	v_cvt_pk_bf16_f32 v118, v124, v125
	v_cvt_pk_bf16_f32 v119, v126, v127
	v_cvt_pk_bf16_f32 v120, v128, v129
	v_cvt_pk_bf16_f32 v121, v130, v131
	v_mfma_f32_32x32x16_bf16 v[80:95], v[10:13], v[156:159], v[80:95]
	v_cvt_pk_bf16_f32 v122, v132, v133
	v_cvt_pk_bf16_f32 v123, v134, v135
	v_cvt_pk_bf16_f32 v124, v136, v137
	v_cvt_pk_bf16_f32 v125, v138, v139
	v_mfma_f32_32x32x16_bf16 v[96:111], v[182:185], v[156:159], v[96:111]
	v_cvt_pk_bf16_f32 v126, v140, v141
	v_cvt_pk_bf16_f32 v127, v142, v143
	s_nop 1
	v_permlane32_swap_b32_e32 v15, v195
	v_permlane32_swap_b32_e32 v112, v114
	v_permlane32_swap_b32_e32 v113, v115
	v_permlane32_swap_b32_e32 v116, v118
	v_permlane32_swap_b32_e32 v117, v119
	v_permlane32_swap_b32_e32 v120, v122
	v_permlane32_swap_b32_e32 v121, v123
	v_permlane32_swap_b32_e32 v124, v126
	v_permlane32_swap_b32_e32 v125, v127
	v_add_f32_e32 v15, v15, v195
	v_fmac_f32_e32 v15, v192, v194
	v_mov_b32_e32 v192, v15
	s_add_i32 s0, s10, 0x8000
	s_and_b32 s0, s0, 0x18000
	v_add_u32_e32 v13, s0, v191
	ds_read_b64_tr_b16 v[128:129], v13 offset:0
	ds_read_b64_tr_b16 v[130:131], v13 offset:2048
	ds_read_b64_tr_b16 v[132:133], v13 offset:512
	ds_read_b64_tr_b16 v[134:135], v13 offset:2560
	ds_read_b64_tr_b16 v[136:137], v13 offset:1024
	ds_read_b64_tr_b16 v[138:139], v13 offset:3072
	ds_read_b64_tr_b16 v[140:141], v13 offset:1536
	ds_read_b64_tr_b16 v[142:143], v13 offset:3584

.Lnl_nors_dr:
	s_waitcnt lgkmcnt(0)
	v_mfma_f32_32x32x16_bf16 v[64:79], v[128:131], v[112:115], v[64:79]
	ds_read_b64_tr_b16 v[160:161], v13 offset:4096
	ds_read_b64_tr_b16 v[162:163], v13 offset:6144
	ds_read_b64_tr_b16 v[182:183], v13 offset:4608
	ds_read_b64_tr_b16 v[184:185], v13 offset:6656
	ds_read_b64_tr_b16 v[198:199], v13 offset:5120
	ds_read_b64_tr_b16 v[200:201], v13 offset:7168
	ds_read_b64_tr_b16 v[202:203], v13 offset:5632
	ds_read_b64_tr_b16 v[204:205], v13 offset:7680
	v_mfma_f32_32x32x16_bf16 v[48:63], v[132:135], v[112:115], v[48:63]
	v_mfma_f32_32x32x16_bf16 v[32:47], v[136:139], v[112:115], v[32:47]
	v_mfma_f32_32x32x16_bf16 v[16:31], v[140:143], v[112:115], v[16:31]
	s_waitcnt lgkmcnt(0)
	v_mfma_f32_32x32x16_bf16 v[64:79], v[160:163], v[116:119], v[64:79]
	ds_read_b64_tr_b16 v[128:129], v13 offset:8192
	ds_read_b64_tr_b16 v[130:131], v13 offset:10240
	ds_read_b64_tr_b16 v[132:133], v13 offset:8704
	ds_read_b64_tr_b16 v[134:135], v13 offset:10752
	ds_read_b64_tr_b16 v[136:137], v13 offset:9216
	ds_read_b64_tr_b16 v[138:139], v13 offset:11264
	ds_read_b64_tr_b16 v[140:141], v13 offset:9728
	ds_read_b64_tr_b16 v[142:143], v13 offset:11776
	v_mfma_f32_32x32x16_bf16 v[48:63], v[182:185], v[116:119], v[48:63]
	v_mfma_f32_32x32x16_bf16 v[32:47], v[198:201], v[116:119], v[32:47]
	v_mfma_f32_32x32x16_bf16 v[16:31], v[202:205], v[116:119], v[16:31]
	s_waitcnt lgkmcnt(0)
	v_mfma_f32_32x32x16_bf16 v[64:79], v[128:131], v[120:123], v[64:79]
	ds_read_b64_tr_b16 v[160:161], v13 offset:12288
	ds_read_b64_tr_b16 v[162:163], v13 offset:14336
	ds_read_b64_tr_b16 v[182:183], v13 offset:12800
	ds_read_b64_tr_b16 v[184:185], v13 offset:14848
	ds_read_b64_tr_b16 v[198:199], v13 offset:13312
	ds_read_b64_tr_b16 v[200:201], v13 offset:15360
	ds_read_b64_tr_b16 v[202:203], v13 offset:13824
	ds_read_b64_tr_b16 v[204:205], v13 offset:15872
	v_mfma_f32_32x32x16_bf16 v[48:63], v[132:135], v[120:123], v[48:63]
	v_mfma_f32_32x32x16_bf16 v[32:47], v[136:139], v[120:123], v[32:47]
	v_mfma_f32_32x32x16_bf16 v[16:31], v[140:143], v[120:123], v[16:31]
	s_waitcnt lgkmcnt(0)
	v_mfma_f32_32x32x16_bf16 v[64:79], v[160:163], v[124:127], v[64:79]
	v_mfma_f32_32x32x16_bf16 v[48:63], v[182:185], v[124:127], v[48:63]
	v_mfma_f32_32x32x16_bf16 v[32:47], v[198:201], v[124:127], v[32:47]
	v_mfma_f32_32x32x16_bf16 v[16:31], v[202:205], v[124:127], v[16:31]
.Lnl_done:
	s_waitcnt lgkmcnt(0)
	s_nop 7
	s_nop 7
